# v57 plus removal of two mid-burst lgkmcnt(0) waits in the in-proj and out-proj GEMM fragment loads (covered by the pre-barrier wait)
# speedup vs baseline: 1.0229x; 1.0016x over previous
; #define PG8_STAGE(bufoff, gbase, voff) do { _Pragma("unroll") for (int _i = 0; _i < 2; ++_i) \
;         __builtin_amdgcn_global_load_lds((const unsigned*)((const char*)(gbase) + (voff)[_i]), (PG8_LAS unsigned*)(lds + (bufoff) + ldsw + _i * 8192), 16, 0, 0); } while (0)
; #define PG8_LDA(dst, b, h) do { _Pragma("unroll") for (int m = 0; m < 4; ++m) _Pragma("unroll") for (int k = 0; k < 2; ++k) dst[m][k] = *(const PG8_LAS bf16x8*)(lds + PG8_SA(b, h) + aoff + m * 2048 + k * 1024); } while (0)
; #define PG8_LDB(dst, b, h) do { _Pragma("unroll") for (int n = 0; n < 2; ++n) _Pragma("unroll") for (int k = 0; k < 2; ++k) dst[n][k] = *(const PG8_LAS bf16x8*)(lds + PG8_SB(b, h) + boff + n * 2048 + k * 1024); } while (0)
; #define PG8_MMA(ai, bj, At, Bt) do { __builtin_amdgcn_s_setprio(1); _Pragma("unroll") for (int m = 0; m < 4; ++m) _Pragma("unroll") for (int n = 0; n < 2; ++n) _Pragma("unroll") for (int k = 0; k < 2; ++k) \
;         acc[ai][bj][m][n] = __builtin_amdgcn_mfma_f32_16x16x32_bf16(Bt[n][k], At[m][k], acc[ai][bj][m][n], 0, 0, 0); __builtin_amdgcn_s_setprio(0); } while (0)
; #define PG8_WAIT_V(n) asm volatile("s_waitcnt vmcnt(" #n ")" ::: "memory")
; #define PG8_WAIT_L(n) asm volatile("s_waitcnt lgkmcnt(" #n ")" ::: "memory")
; #define PG8_BAR __builtin_amdgcn_s_barrier()
; #define PG8_SCHED __builtin_amdgcn_sched_barrier(0)
; template <class Epi, class Sched, bool ALIGN_EPI = false, bool SP2 = false>
; __device__ __forceinline__ void gemm_phase(PG8_LAS unsigned char* lds, const Gemm g, const Sched& S, const Epi& E, int wv) {
;     ...
;         for (int t = 0; t < nt; t += 2) {
;             const bool last = (t == nt - 2);
;             const char* a1 = cA + (size_t)(t + 1) * kstep;
;             const char* a2 = last ? nA : cA + (size_t)(t + 2) * kstep; const char* b2 = last ? nB : cB + (size_t)(t + 2) * kstep;
;             const char* a3 = a2 + kstep; const char* b3 = b2 + kstep;
;             if (last && has_next) S.a_ready(nxt);
;             if constexpr (SP2) {
;             PG8_LDB(B0, 0, 0); PG8_LDB(B1, 0, 1); PG8_SCHED; PG8_LDA(At, 0, 0); PG8_STAGE(PG8_SA(1, 1), a1 + hstep, voffA);
;             PG8_WAIT_V(8); PG8_WAIT_L(0); PG8_BAR; PG8_MMA(0, 0, At, B0); PG8_MMA(0, 1, At, B1); PG8_BAR; PG8_SCHED;
;             PG8_LDA(At, 0, 1); PG8_STAGE(PG8_SB(0, 0), b2, voffB); PG8_STAGE(PG8_SB(0, 1), b2 + hstep, voffB); PG8_STAGE(PG8_SA(0, 0), a2, voffA);
.LBB0_120:
	s_add_u32 s44, s34, 0xfff80080
	s_addc_u32 s45, s35, -1
	s_add_i32 s52, 0, 0x10000
	s_cmp_eq_u32 s51, 28
	s_cselect_b32 s47, s7, s45
	s_cselect_b32 s46, s21, s44
	s_cselect_b32 s45, s19, s50
	s_cselect_b32 s44, s48, s49
	s_add_i32 s54, 0, 0x14000
	v_add_u32_e32 v152, s52, v189
	v_add_u32_e32 v168, s54, v189
	ds_read_b128 v[128:131], v152
	ds_read_b128 v[132:135], v152 offset:1024
	ds_read_b128 v[148:151], v152 offset:2048
	ds_read_b128 v[152:155], v152 offset:3072
	s_nop 0
	ds_read_b128 v[156:159], v168
	ds_read_b128 v[160:163], v168 offset:1024
	ds_read_b128 v[164:167], v168 offset:2048
	ds_read_b128 v[168:171], v168 offset:3072
	v_lshl_add_u64 v[178:179], s[34:35], 0, v[144:145]
	s_add_i32 m0, s11, 0xc000
	ds_read_b128 v[172:175], v192
	ds_read_b128 v[194:197], v192 offset:1024
	ds_read_b128 v[198:201], v192 offset:2048
	ds_read_b128 v[202:205], v192 offset:3072
	ds_read_b128 v[206:209], v192 offset:4096
	ds_read_b128 v[210:213], v192 offset:5120
	ds_read_b128 v[214:217], v192 offset:6144
	ds_read_b128 v[218:221], v192 offset:7168
	global_load_lds_dwordx4 v[178:179], off
	v_lshl_add_u64 v[178:179], s[34:35], 0, v[146:147]
	s_add_i32 m0, s11, 0xe000
	s_nop 0
	global_load_lds_dwordx4 v[178:179], off
	s_waitcnt vmcnt(8)
	s_waitcnt lgkmcnt(0)
	s_barrier
	s_setprio 1
	s_waitcnt lgkmcnt(0)
	v_mfma_f32_16x16x32_bf16 v[124:127], v[128:131], v[172:175], v[124:127]
	v_mfma_f32_16x16x32_bf16 v[120:123], v[148:151], v[172:175], v[120:123]
	v_mfma_f32_16x16x32_bf16 v[112:115], v[128:131], v[198:201], v[112:115]
	v_mfma_f32_16x16x32_bf16 v[104:107], v[148:151], v[198:201], v[104:107]
	v_mfma_f32_16x16x32_bf16 v[96:99], v[128:131], v[206:209], v[96:99]
	v_mfma_f32_16x16x32_bf16 v[88:91], v[148:151], v[206:209], v[88:91]
	v_mfma_f32_16x16x32_bf16 v[80:83], v[128:131], v[214:217], v[80:83]
	v_mfma_f32_16x16x32_bf16 v[72:75], v[148:151], v[214:217], v[72:75]
	v_mfma_f32_16x16x32_bf16 v[124:127], v[132:135], v[194:197], v[124:127]
	v_mfma_f32_16x16x32_bf16 v[120:123], v[152:155], v[194:197], v[120:123]
	v_mfma_f32_16x16x32_bf16 v[112:115], v[132:135], v[202:205], v[112:115]
	v_mfma_f32_16x16x32_bf16 v[104:107], v[152:155], v[202:205], v[104:107]
	v_mfma_f32_16x16x32_bf16 v[96:99], v[132:135], v[210:213], v[96:99]
	v_mfma_f32_16x16x32_bf16 v[88:91], v[152:155], v[210:213], v[88:91]
	v_mfma_f32_16x16x32_bf16 v[80:83], v[132:135], v[218:221], v[80:83]
	v_mfma_f32_16x16x32_bf16 v[72:75], v[152:155], v[218:221], v[72:75]
	s_setprio 0
	s_setprio 1
	v_mfma_f32_16x16x32_bf16 v[116:119], v[156:159], v[172:175], v[116:119]
	v_mfma_f32_16x16x32_bf16 v[108:111], v[164:167], v[172:175], v[108:111]
	v_mfma_f32_16x16x32_bf16 v[100:103], v[156:159], v[198:201], v[100:103]
	v_mfma_f32_16x16x32_bf16 v[92:95], v[164:167], v[198:201], v[92:95]
	v_mfma_f32_16x16x32_bf16 v[84:87], v[156:159], v[206:209], v[84:87]
	v_mfma_f32_16x16x32_bf16 v[76:79], v[164:167], v[206:209], v[76:79]
	v_mfma_f32_16x16x32_bf16 v[68:71], v[156:159], v[214:217], v[68:71]
	v_mfma_f32_16x16x32_bf16 v[64:67], v[164:167], v[214:217], v[64:67]
	v_mfma_f32_16x16x32_bf16 v[116:119], v[160:163], v[194:197], v[116:119]
	v_mfma_f32_16x16x32_bf16 v[108:111], v[168:171], v[194:197], v[108:111]
	v_mfma_f32_16x16x32_bf16 v[100:103], v[160:163], v[202:205], v[100:103]
	v_mfma_f32_16x16x32_bf16 v[92:95], v[168:171], v[202:205], v[92:95]
	v_mfma_f32_16x16x32_bf16 v[84:87], v[160:163], v[210:213], v[84:87]
	v_mfma_f32_16x16x32_bf16 v[76:79], v[168:171], v[210:213], v[76:79]
	v_mfma_f32_16x16x32_bf16 v[68:71], v[160:163], v[218:221], v[68:71]
	v_mfma_f32_16x16x32_bf16 v[64:67], v[168:171], v[218:221], v[64:67]
	s_setprio 0
	s_barrier
	s_add_i32 s52, s52, s0
	v_lshl_add_u64 v[178:179], s[44:45], 0, v[176:177]
	s_mov_b32 m0, s52
	ds_read_b128 v[172:175], v192 offset:16384
	ds_read_b128 v[194:197], v192 offset:17408
	ds_read_b128 v[198:201], v192 offset:18432
	ds_read_b128 v[202:205], v192 offset:19456
	ds_read_b128 v[206:209], v192 offset:20480
	ds_read_b128 v[210:213], v192 offset:21504
	ds_read_b128 v[214:217], v192 offset:22528
	ds_read_b128 v[218:221], v192 offset:23552
	global_load_lds_dwordx4 v[178:179], off
	s_add_i32 m0, s52, 0x2000
	s_add_u32 s52, s44, 0x80000
	v_lshl_add_u64 v[180:181], s[44:45], 0, v[136:137]
	s_addc_u32 s53, s45, 0
	s_add_i32 s54, s54, s0
	global_load_lds_dwordx4 v[180:181], off
	v_lshl_add_u64 v[182:183], s[52:53], 0, v[176:177]
	s_mov_b32 m0, s54
	v_lshl_add_u64 v[184:185], s[46:47], 0, v[138:139]
	global_load_lds_dwordx4 v[182:183], off
	v_lshl_add_u64 v[182:183], s[52:53], 0, v[136:137]
	s_add_i32 m0, s54, 0x2000
	s_nop 0
	global_load_lds_dwordx4 v[182:183], off
	v_lshl_add_u64 v[182:183], s[46:47], 0, v[140:141]
	s_mov_b32 m0, s11
	s_nop 0
	global_load_lds_dwordx4 v[182:183], off
	s_mov_b32 m0, s22
	s_nop 0
	global_load_lds_dwordx4 v[184:185], off
	s_waitcnt vmcnt(8)
	s_waitcnt lgkmcnt(0)
	s_barrier
; #define PG8_STAGE(bufoff, gbase, voff) do { _Pragma("unroll") for (int _i = 0; _i < 2; ++_i) \
;         __builtin_amdgcn_global_load_lds((const unsigned*)((const char*)(gbase) + (voff)[_i]), (PG8_LAS unsigned*)(lds + (bufoff) + ldsw + _i * 8192), 16, 0, 0); } while (0)
; #define PG8_LDA(dst, b, h) do { _Pragma("unroll") for (int m = 0; m < 4; ++m) _Pragma("unroll") for (int k = 0; k < 2; ++k) dst[m][k] = *(const PG8_LAS bf16x8*)(lds + PG8_SA(b, h) + aoff + m * 2048 + k * 1024); } while (0)
; #define PG8_LDB(dst, b, h) do { _Pragma("unroll") for (int n = 0; n < 2; ++n) _Pragma("unroll") for (int k = 0; k < 2; ++k) dst[n][k] = *(const PG8_LAS bf16x8*)(lds + PG8_SB(b, h) + boff + n * 2048 + k * 1024); } while (0)
; #define PG8_MMA(ai, bj, At, Bt) do { __builtin_amdgcn_s_setprio(1); _Pragma("unroll") for (int m = 0; m < 4; ++m) _Pragma("unroll") for (int n = 0; n < 2; ++n) _Pragma("unroll") for (int k = 0; k < 2; ++k) \
;         acc[ai][bj][m][n] = __builtin_amdgcn_mfma_f32_16x16x32_bf16(Bt[n][k], At[m][k], acc[ai][bj][m][n], 0, 0, 0); __builtin_amdgcn_s_setprio(0); } while (0)
; #define PG8_WAIT_V(n) asm volatile("s_waitcnt vmcnt(" #n ")" ::: "memory")
; #define PG8_WAIT_L(n) asm volatile("s_waitcnt lgkmcnt(" #n ")" ::: "memory")
; #define PG8_BAR __builtin_amdgcn_s_barrier()
; #define PG8_SCHED __builtin_amdgcn_sched_barrier(0)
; template <class Epi, class Sched, bool ALIGN_EPI = false, bool SP2 = false>
; __device__ __forceinline__ void gemm_phase(PG8_LAS unsigned char* lds, const Gemm g, const Sched& S, const Epi& E, int wv) {
;     ...
;             PG8_WAIT_V(8); PG8_WAIT_L(0); PG8_BAR; PG8_MMA(0, 0, At, B0); PG8_MMA(0, 1, At, B1); PG8_BAR; PG8_SCHED;
;             PG8_LDA(At, 0, 1); PG8_STAGE(PG8_SB(0, 0), b2, voffB); PG8_STAGE(PG8_SB(0, 1), b2 + hstep, voffB); PG8_STAGE(PG8_SA(0, 0), a2, voffA);
;             PG8_WAIT_V(8); PG8_WAIT_L(0); PG8_BAR; PG8_MMA(1, 0, At, B0); PG8_MMA(1, 1, At, B1); PG8_BAR; PG8_SCHED;
;             PG8_LDB(B0, 1, 0); PG8_LDB(B1, 1, 1); PG8_SCHED; PG8_LDA(At, 1, 0); PG8_STAGE(PG8_SA(0, 1), a2 + hstep, voffA);
;             PG8_WAIT_V(8); PG8_WAIT_L(0); PG8_BAR; PG8_MMA(0, 0, At, B0); PG8_MMA(0, 1, At, B1); PG8_BAR; PG8_SCHED;
;             PG8_LDA(At, 1, 1); PG8_STAGE(PG8_SB(1, 0), b3, voffB); PG8_STAGE(PG8_SB(1, 1), b3 + hstep, voffB); PG8_STAGE(PG8_SA(1, 0), a3, voffA);
	s_setprio 1
	s_waitcnt lgkmcnt(0)
	v_mfma_f32_16x16x32_bf16 v[60:63], v[128:131], v[172:175], v[60:63]
	v_mfma_f32_16x16x32_bf16 v[56:59], v[148:151], v[172:175], v[56:59]
	v_mfma_f32_16x16x32_bf16 v[48:51], v[128:131], v[198:201], v[48:51]
	v_mfma_f32_16x16x32_bf16 v[40:43], v[148:151], v[198:201], v[40:43]
	v_mfma_f32_16x16x32_bf16 v[32:35], v[128:131], v[206:209], v[32:35]
	v_mfma_f32_16x16x32_bf16 v[24:27], v[148:151], v[206:209], v[24:27]
	v_mfma_f32_16x16x32_bf16 v[16:19], v[128:131], v[214:217], v[16:19]
	v_mfma_f32_16x16x32_bf16 v[8:11], v[148:151], v[214:217], v[8:11]
	v_mfma_f32_16x16x32_bf16 v[60:63], v[132:135], v[194:197], v[60:63]
	v_mfma_f32_16x16x32_bf16 v[56:59], v[152:155], v[194:197], v[56:59]
	v_mfma_f32_16x16x32_bf16 v[48:51], v[132:135], v[202:205], v[48:51]
	v_mfma_f32_16x16x32_bf16 v[40:43], v[152:155], v[202:205], v[40:43]
	v_mfma_f32_16x16x32_bf16 v[32:35], v[132:135], v[210:213], v[32:35]
	v_mfma_f32_16x16x32_bf16 v[24:27], v[152:155], v[210:213], v[24:27]
	v_mfma_f32_16x16x32_bf16 v[16:19], v[132:135], v[218:221], v[16:19]
	v_mfma_f32_16x16x32_bf16 v[8:11], v[152:155], v[218:221], v[8:11]
	s_setprio 0
	s_setprio 1
	v_mfma_f32_16x16x32_bf16 v[52:55], v[156:159], v[172:175], v[52:55]
	v_mfma_f32_16x16x32_bf16 v[44:47], v[164:167], v[172:175], v[44:47]
	v_mfma_f32_16x16x32_bf16 v[36:39], v[156:159], v[198:201], v[36:39]
	v_mfma_f32_16x16x32_bf16 v[28:31], v[164:167], v[198:201], v[28:31]
	v_mfma_f32_16x16x32_bf16 v[20:23], v[156:159], v[206:209], v[20:23]
	v_mfma_f32_16x16x32_bf16 v[12:15], v[164:167], v[206:209], v[12:15]
	v_mfma_f32_16x16x32_bf16 v[4:7], v[156:159], v[214:217], v[4:7]
	v_mfma_f32_16x16x32_bf16 v[0:3], v[164:167], v[214:217], v[0:3]
	v_mfma_f32_16x16x32_bf16 v[52:55], v[160:163], v[194:197], v[52:55]
	v_mfma_f32_16x16x32_bf16 v[44:47], v[168:171], v[194:197], v[44:47]
	v_mfma_f32_16x16x32_bf16 v[36:39], v[160:163], v[202:205], v[36:39]
	v_mfma_f32_16x16x32_bf16 v[28:31], v[168:171], v[202:205], v[28:31]
	v_mfma_f32_16x16x32_bf16 v[20:23], v[160:163], v[210:213], v[20:23]
	v_mfma_f32_16x16x32_bf16 v[12:15], v[168:171], v[210:213], v[12:15]
	v_mfma_f32_16x16x32_bf16 v[4:7], v[160:163], v[218:221], v[4:7]
	v_mfma_f32_16x16x32_bf16 v[0:3], v[168:171], v[218:221], v[0:3]
	s_setprio 0
	s_barrier
	s_add_i32 s52, 0, 0x18000
	s_add_i32 s53, 0, 0x1c000
	v_add_u32_e32 v152, s52, v189
	v_add_u32_e32 v168, s53, v189
	ds_read_b128 v[128:131], v152
	ds_read_b128 v[132:135], v152 offset:1024
	ds_read_b128 v[148:151], v152 offset:2048
	ds_read_b128 v[152:155], v152 offset:3072
	ds_read_b128 v[156:159], v168
	ds_read_b128 v[160:163], v168 offset:1024
	ds_read_b128 v[164:167], v168 offset:2048
	ds_read_b128 v[168:171], v168 offset:3072
	s_add_u32 s46, s46, 0x80000
	s_addc_u32 s47, s47, 0
	s_mov_b32 m0, s23
	v_lshl_add_u64 v[186:187], s[46:47], 0, v[140:141]
	ds_read_b128 v[172:175], v192 offset:32768
	ds_read_b128 v[194:197], v192 offset:33792
	ds_read_b128 v[198:201], v192 offset:34816
	ds_read_b128 v[202:205], v192 offset:35840
	ds_read_b128 v[206:209], v192 offset:36864
	ds_read_b128 v[210:213], v192 offset:37888
	ds_read_b128 v[214:217], v192 offset:38912
	ds_read_b128 v[218:221], v192 offset:39936
	global_load_lds_dwordx4 v[186:187], off
	v_lshl_add_u64 v[186:187], s[46:47], 0, v[138:139]
	s_mov_b32 m0, s24
	s_nop 0
	global_load_lds_dwordx4 v[186:187], off
	s_waitcnt vmcnt(8)
	s_waitcnt lgkmcnt(0)
	s_barrier
	s_setprio 1
	s_waitcnt lgkmcnt(0)
	v_mfma_f32_16x16x32_bf16 v[124:127], v[128:131], v[172:175], v[124:127]
	v_mfma_f32_16x16x32_bf16 v[120:123], v[148:151], v[172:175], v[120:123]
	v_mfma_f32_16x16x32_bf16 v[112:115], v[128:131], v[198:201], v[112:115]
	v_mfma_f32_16x16x32_bf16 v[104:107], v[148:151], v[198:201], v[104:107]
	v_mfma_f32_16x16x32_bf16 v[96:99], v[128:131], v[206:209], v[96:99]
	v_mfma_f32_16x16x32_bf16 v[88:91], v[148:151], v[206:209], v[88:91]
	v_mfma_f32_16x16x32_bf16 v[80:83], v[128:131], v[214:217], v[80:83]
	v_mfma_f32_16x16x32_bf16 v[72:75], v[148:151], v[214:217], v[72:75]
	v_mfma_f32_16x16x32_bf16 v[124:127], v[132:135], v[194:197], v[124:127]
	v_mfma_f32_16x16x32_bf16 v[120:123], v[152:155], v[194:197], v[120:123]
	v_mfma_f32_16x16x32_bf16 v[112:115], v[132:135], v[202:205], v[112:115]
	v_mfma_f32_16x16x32_bf16 v[104:107], v[152:155], v[202:205], v[104:107]
	v_mfma_f32_16x16x32_bf16 v[96:99], v[132:135], v[210:213], v[96:99]
	v_mfma_f32_16x16x32_bf16 v[88:91], v[152:155], v[210:213], v[88:91]
	v_mfma_f32_16x16x32_bf16 v[80:83], v[132:135], v[218:221], v[80:83]
	v_mfma_f32_16x16x32_bf16 v[72:75], v[152:155], v[218:221], v[72:75]
	s_setprio 0
	s_setprio 1
	v_mfma_f32_16x16x32_bf16 v[116:119], v[156:159], v[172:175], v[116:119]
	v_mfma_f32_16x16x32_bf16 v[108:111], v[164:167], v[172:175], v[108:111]
	v_mfma_f32_16x16x32_bf16 v[100:103], v[156:159], v[198:201], v[100:103]
	v_mfma_f32_16x16x32_bf16 v[92:95], v[164:167], v[198:201], v[92:95]
	v_mfma_f32_16x16x32_bf16 v[84:87], v[156:159], v[206:209], v[84:87]
	v_mfma_f32_16x16x32_bf16 v[76:79], v[164:167], v[206:209], v[76:79]
	v_mfma_f32_16x16x32_bf16 v[68:71], v[156:159], v[214:217], v[68:71]
	v_mfma_f32_16x16x32_bf16 v[64:67], v[164:167], v[214:217], v[64:67]
	v_mfma_f32_16x16x32_bf16 v[116:119], v[160:163], v[194:197], v[116:119]
	v_mfma_f32_16x16x32_bf16 v[108:111], v[168:171], v[194:197], v[108:111]
	v_mfma_f32_16x16x32_bf16 v[100:103], v[160:163], v[202:205], v[100:103]
	v_mfma_f32_16x16x32_bf16 v[92:95], v[168:171], v[202:205], v[92:95]
	v_mfma_f32_16x16x32_bf16 v[84:87], v[160:163], v[210:213], v[84:87]
	v_mfma_f32_16x16x32_bf16 v[76:79], v[168:171], v[210:213], v[76:79]
	v_mfma_f32_16x16x32_bf16 v[68:71], v[160:163], v[218:221], v[68:71]
	v_mfma_f32_16x16x32_bf16 v[64:67], v[168:171], v[218:221], v[64:67]
	s_setprio 0
	s_barrier
; #define PG8_STAGE(bufoff, gbase, voff) do { _Pragma("unroll") for (int _i = 0; _i < 2; ++_i) \
;         __builtin_amdgcn_global_load_lds((const unsigned*)((const char*)(gbase) + (voff)[_i]), (PG8_LAS unsigned*)(lds + (bufoff) + ldsw + _i * 8192), 16, 0, 0); } while (0)
; #define PG8_LDA(dst, b, h) do { _Pragma("unroll") for (int m = 0; m < 4; ++m) _Pragma("unroll") for (int k = 0; k < 2; ++k) dst[m][k] = *(const PG8_LAS bf16x8*)(lds + PG8_SA(b, h) + aoff + m * 2048 + k * 1024); } while (0)
; #define PG8_LDB(dst, b, h) do { _Pragma("unroll") for (int n = 0; n < 2; ++n) _Pragma("unroll") for (int k = 0; k < 2; ++k) dst[n][k] = *(const PG8_LAS bf16x8*)(lds + PG8_SB(b, h) + boff + n * 2048 + k * 1024); } while (0)
; template <class Epi, class Sched, bool ALIGN_EPI = false, bool SP2 = false>
; __device__ __forceinline__ void gemm_phase(PG8_LAS unsigned char* lds, const Gemm g, const Sched& S, const Epi& E, int wv) {
;     ...
;         for (int t = 0; t < nt; t += 2) {
;             const bool last = (t == nt - 2);
;             const char* a1 = cA + (size_t)(t + 1) * kstep;
;             const char* a2 = last ? nA : cA + (size_t)(t + 2) * kstep; const char* b2 = last ? nB : cB + (size_t)(t + 2) * kstep;
;             const char* a3 = a2 + kstep; const char* b3 = b2 + kstep;
;             if (last && has_next) S.a_ready(nxt);
;             if constexpr (SP2) {
;             PG8_LDB(B0, 0, 0); PG8_LDB(B1, 0, 1); PG8_SCHED; PG8_LDA(At, 0, 0); PG8_STAGE(PG8_SA(1, 1), a1 + hstep, voffA);
;             PG8_WAIT_V(8); PG8_WAIT_L(0); PG8_BAR; PG8_MMA(0, 0, At, B0); PG8_MMA(0, 1, At, B1); PG8_BAR; PG8_SCHED;
;             PG8_LDA(At, 0, 1); PG8_STAGE(PG8_SB(0, 0), b2, voffB); PG8_STAGE(PG8_SB(0, 1), b2 + hstep, voffB); PG8_STAGE(PG8_SA(0, 0), a2, voffA);
;             PG8_WAIT_V(8); PG8_WAIT_L(0); PG8_BAR; PG8_MMA(1, 0, At, B0); PG8_MMA(1, 1, At, B1); PG8_BAR; PG8_SCHED;
;             PG8_LDB(B0, 1, 0); PG8_LDB(B1, 1, 1); PG8_SCHED; PG8_LDA(At, 1, 0); PG8_STAGE(PG8_SA(0, 1), a2 + hstep, voffA);
;             PG8_WAIT_V(8); PG8_WAIT_L(0); PG8_BAR; PG8_MMA(0, 0, At, B0); PG8_MMA(0, 1, At, B1); PG8_BAR; PG8_SCHED;
;             PG8_LDA(At, 1, 1); PG8_STAGE(PG8_SB(1, 0), b3, voffB); PG8_STAGE(PG8_SB(1, 1), b3 + hstep, voffB); PG8_STAGE(PG8_SA(1, 0), a3, voffA);
;             PG8_WAIT_V(8); PG8_WAIT_L(0); PG8_BAR; PG8_MMA(1, 0, At, B0); PG8_MMA(1, 1, At, B1); PG8_BAR; PG8_SCHED;
	s_add_i32 s46, s52, s0
	v_lshl_add_u64 v[178:179], v[178:179], 0, s[28:29]
	s_mov_b32 m0, s46
	ds_read_b128 v[172:175], v192 offset:49152
	ds_read_b128 v[194:197], v192 offset:50176
	ds_read_b128 v[198:201], v192 offset:51200
	ds_read_b128 v[202:205], v192 offset:52224
	ds_read_b128 v[206:209], v192 offset:53248
	ds_read_b128 v[210:213], v192 offset:54272
	ds_read_b128 v[214:217], v192 offset:55296
	ds_read_b128 v[218:221], v192 offset:56320
	global_load_lds_dwordx4 v[178:179], off
	s_add_i32 m0, s46, 0x2000
	s_add_u32 s44, s44, 0x80080
	v_lshl_add_u64 v[178:179], v[180:181], 0, s[28:29]
	s_addc_u32 s45, s45, 0
	s_add_i32 s46, s53, s0
	global_load_lds_dwordx4 v[178:179], off
	v_lshl_add_u64 v[178:179], s[44:45], 0, v[176:177]
	s_mov_b32 m0, s46
	s_nop 0
	global_load_lds_dwordx4 v[178:179], off
	v_lshl_add_u64 v[178:179], s[44:45], 0, v[136:137]
	s_add_i32 m0, s46, 0x2000
	s_nop 0
	global_load_lds_dwordx4 v[178:179], off
	v_lshl_add_u64 v[178:179], v[182:183], 0, s[28:29]
	s_mov_b32 m0, s25
	s_nop 0
	global_load_lds_dwordx4 v[178:179], off
	v_lshl_add_u64 v[178:179], v[184:185], 0, s[28:29]
	s_mov_b32 m0, s27
	s_nop 0
	global_load_lds_dwordx4 v[178:179], off
	s_waitcnt vmcnt(8)
	s_waitcnt lgkmcnt(0)
	s_barrier
	s_setprio 1
	s_waitcnt lgkmcnt(0)
	v_mfma_f32_16x16x32_bf16 v[60:63], v[128:131], v[172:175], v[60:63]
	v_mfma_f32_16x16x32_bf16 v[56:59], v[148:151], v[172:175], v[56:59]
	v_mfma_f32_16x16x32_bf16 v[48:51], v[128:131], v[198:201], v[48:51]
	v_mfma_f32_16x16x32_bf16 v[40:43], v[148:151], v[198:201], v[40:43]
	v_mfma_f32_16x16x32_bf16 v[32:35], v[128:131], v[206:209], v[32:35]
	v_mfma_f32_16x16x32_bf16 v[24:27], v[148:151], v[206:209], v[24:27]
	v_mfma_f32_16x16x32_bf16 v[16:19], v[128:131], v[214:217], v[16:19]
	v_mfma_f32_16x16x32_bf16 v[8:11], v[148:151], v[214:217], v[8:11]
	v_mfma_f32_16x16x32_bf16 v[60:63], v[132:135], v[194:197], v[60:63]
	v_mfma_f32_16x16x32_bf16 v[56:59], v[152:155], v[194:197], v[56:59]
	v_mfma_f32_16x16x32_bf16 v[48:51], v[132:135], v[202:205], v[48:51]
	v_mfma_f32_16x16x32_bf16 v[40:43], v[152:155], v[202:205], v[40:43]
	v_mfma_f32_16x16x32_bf16 v[32:35], v[132:135], v[210:213], v[32:35]
	v_mfma_f32_16x16x32_bf16 v[24:27], v[152:155], v[210:213], v[24:27]
	v_mfma_f32_16x16x32_bf16 v[16:19], v[132:135], v[218:221], v[16:19]
	v_mfma_f32_16x16x32_bf16 v[8:11], v[152:155], v[218:221], v[8:11]
	s_setprio 0
	s_setprio 1
	v_mfma_f32_16x16x32_bf16 v[52:55], v[156:159], v[172:175], v[52:55]
	v_mfma_f32_16x16x32_bf16 v[44:47], v[164:167], v[172:175], v[44:47]
	v_mfma_f32_16x16x32_bf16 v[36:39], v[156:159], v[198:201], v[36:39]
	v_mfma_f32_16x16x32_bf16 v[28:31], v[164:167], v[198:201], v[28:31]
	v_mfma_f32_16x16x32_bf16 v[20:23], v[156:159], v[206:209], v[20:23]
	v_mfma_f32_16x16x32_bf16 v[12:15], v[164:167], v[206:209], v[12:15]
	v_mfma_f32_16x16x32_bf16 v[4:7], v[156:159], v[214:217], v[4:7]
	v_mfma_f32_16x16x32_bf16 v[0:3], v[164:167], v[214:217], v[0:3]
	v_mfma_f32_16x16x32_bf16 v[52:55], v[160:163], v[194:197], v[52:55]
	v_mfma_f32_16x16x32_bf16 v[44:47], v[168:171], v[194:197], v[44:47]
	v_mfma_f32_16x16x32_bf16 v[36:39], v[160:163], v[202:205], v[36:39]
	v_mfma_f32_16x16x32_bf16 v[28:31], v[168:171], v[202:205], v[28:31]
	v_mfma_f32_16x16x32_bf16 v[20:23], v[160:163], v[210:213], v[20:23]
	v_mfma_f32_16x16x32_bf16 v[12:15], v[168:171], v[210:213], v[12:15]
	v_mfma_f32_16x16x32_bf16 v[4:7], v[160:163], v[218:221], v[4:7]
	v_mfma_f32_16x16x32_bf16 v[0:3], v[168:171], v[218:221], v[0:3]
	s_setprio 0
	s_barrier
	s_add_i32 s51, s51, 2
	s_add_u32 s34, s34, 0x100
	s_addc_u32 s35, s35, 0
	s_add_u32 s49, s49, 0x100
	s_addc_u32 s50, s50, 0
	s_cmp_gt_u32 s51, 29
	s_cbranch_scc0 .LBB0_120
	s_and_b64 vcc, exec, s[14:15]
	s_cbranch_vccz .LBB0_123
	s_barrier

; #define PG8_STAGE(bufoff, gbase, voff) do { _Pragma("unroll") for (int _i = 0; _i < 2; ++_i) \
;         __builtin_amdgcn_global_load_lds((const unsigned*)((const char*)(gbase) + (voff)[_i]), (PG8_LAS unsigned*)(lds + (bufoff) + ldsw + _i * 8192), 16, 0, 0); } while (0)
; #define PG8_LDA(dst, b, h) do { _Pragma("unroll") for (int m = 0; m < 4; ++m) _Pragma("unroll") for (int k = 0; k < 2; ++k) dst[m][k] = *(const PG8_LAS bf16x8*)(lds + PG8_SA(b, h) + aoff + m * 2048 + k * 1024); } while (0)
; #define PG8_LDB(dst, b, h) do { _Pragma("unroll") for (int n = 0; n < 2; ++n) _Pragma("unroll") for (int k = 0; k < 2; ++k) dst[n][k] = *(const PG8_LAS bf16x8*)(lds + PG8_SB(b, h) + boff + n * 2048 + k * 1024); } while (0)
; #define PG8_MMA(ai, bj, At, Bt) do { __builtin_amdgcn_s_setprio(1); _Pragma("unroll") for (int m = 0; m < 4; ++m) _Pragma("unroll") for (int n = 0; n < 2; ++n) _Pragma("unroll") for (int k = 0; k < 2; ++k) \
;         acc[ai][bj][m][n] = __builtin_amdgcn_mfma_f32_16x16x32_bf16(Bt[n][k], At[m][k], acc[ai][bj][m][n], 0, 0, 0); __builtin_amdgcn_s_setprio(0); } while (0)
; #define PG8_WAIT_V(n) asm volatile("s_waitcnt vmcnt(" #n ")" ::: "memory")
; #define PG8_WAIT_L(n) asm volatile("s_waitcnt lgkmcnt(" #n ")" ::: "memory")
; #define PG8_BAR __builtin_amdgcn_s_barrier()
; #define PG8_SCHED __builtin_amdgcn_sched_barrier(0)
; template <class Epi, class Sched, bool ALIGN_EPI = false, bool SP2 = false>
; __device__ __forceinline__ void gemm_phase(PG8_LAS unsigned char* lds, const Gemm g, const Sched& S, const Epi& E, int wv) {
;     ...
;         for (int t = 0; t < nt; t += 2) {
;             const bool last = (t == nt - 2);
;             const char* a1 = cA + (size_t)(t + 1) * kstep;
;             const char* a2 = last ? nA : cA + (size_t)(t + 2) * kstep; const char* b2 = last ? nB : cB + (size_t)(t + 2) * kstep;
;             const char* a3 = a2 + kstep; const char* b3 = b2 + kstep;
;             if (last && has_next) S.a_ready(nxt);
;             if constexpr (SP2) {
;             PG8_LDB(B0, 0, 0); PG8_LDB(B1, 0, 1); PG8_SCHED; PG8_LDA(At, 0, 0); PG8_STAGE(PG8_SA(1, 1), a1 + hstep, voffA);
;             PG8_WAIT_V(8); PG8_WAIT_L(0); PG8_BAR; PG8_MMA(0, 0, At, B0); PG8_MMA(0, 1, At, B1); PG8_BAR; PG8_SCHED;
;             PG8_LDA(At, 0, 1); PG8_STAGE(PG8_SB(0, 0), b2, voffB); PG8_STAGE(PG8_SB(0, 1), b2 + hstep, voffB); PG8_STAGE(PG8_SA(0, 0), a2, voffA);
.LBB0_343:
	s_add_u32 s48, s40, 0xfff80080
	s_addc_u32 s49, s41, -1
	s_add_i32 s55, 0, 0x10000
	s_cmp_eq_u32 s54, 28
	s_cselect_b32 s51, s7, s49
	s_cselect_b32 s50, s21, s48
	s_cselect_b32 s49, s19, s53
	s_cselect_b32 s48, s35, s52
	s_add_i32 s58, 0, 0x14000
	v_add_u32_e32 v154, s55, v147
	v_add_u32_e32 v170, s58, v147
	ds_read_b128 v[138:141], v154
	ds_read_b128 v[142:145], v154 offset:1024
	ds_read_b128 v[150:153], v154 offset:2048
	s_nop 0
	ds_read_b128 v[154:157], v154 offset:3072
	ds_read_b128 v[158:161], v170
	ds_read_b128 v[162:165], v170 offset:1024
	ds_read_b128 v[166:169], v170 offset:2048
	ds_read_b128 v[170:173], v170 offset:3072
	v_lshl_add_u64 v[174:175], s[40:41], 0, v[134:135]
	s_add_i32 m0, s3, 0xc000
	ds_read_b128 v[178:181], v149
	ds_read_b128 v[182:185], v149 offset:1024
	ds_read_b128 v[186:189], v149 offset:2048
	ds_read_b128 v[190:193], v149 offset:3072
	ds_read_b128 v[194:197], v149 offset:4096
	ds_read_b128 v[198:201], v149 offset:5120
	ds_read_b128 v[202:205], v149 offset:6144
	ds_read_b128 v[206:209], v149 offset:7168
	global_load_lds_dwordx4 v[174:175], off
	v_lshl_add_u64 v[174:175], s[40:41], 0, v[136:137]
	s_add_i32 m0, s3, 0xe000
	s_nop 0
	global_load_lds_dwordx4 v[174:175], off
	s_waitcnt vmcnt(8)
	s_waitcnt lgkmcnt(0)
	s_barrier
	s_setprio 1
	s_waitcnt lgkmcnt(0)
	v_mfma_f32_16x16x32_bf16 v[124:127], v[138:141], v[178:181], v[124:127]
	v_mfma_f32_16x16x32_bf16 v[120:123], v[150:153], v[178:181], v[120:123]
	v_mfma_f32_16x16x32_bf16 v[108:111], v[138:141], v[186:189], v[108:111]
	v_mfma_f32_16x16x32_bf16 v[104:107], v[150:153], v[186:189], v[104:107]
	v_mfma_f32_16x16x32_bf16 v[92:95], v[138:141], v[194:197], v[92:95]
	v_mfma_f32_16x16x32_bf16 v[88:91], v[150:153], v[194:197], v[88:91]
	v_mfma_f32_16x16x32_bf16 v[76:79], v[138:141], v[202:205], v[76:79]
	v_mfma_f32_16x16x32_bf16 v[72:75], v[150:153], v[202:205], v[72:75]
	v_mfma_f32_16x16x32_bf16 v[124:127], v[142:145], v[182:185], v[124:127]
	v_mfma_f32_16x16x32_bf16 v[120:123], v[154:157], v[182:185], v[120:123]
	v_mfma_f32_16x16x32_bf16 v[108:111], v[142:145], v[190:193], v[108:111]
	v_mfma_f32_16x16x32_bf16 v[104:107], v[154:157], v[190:193], v[104:107]
	v_mfma_f32_16x16x32_bf16 v[92:95], v[142:145], v[198:201], v[92:95]
	v_mfma_f32_16x16x32_bf16 v[88:91], v[154:157], v[198:201], v[88:91]
	v_mfma_f32_16x16x32_bf16 v[76:79], v[142:145], v[206:209], v[76:79]
	v_mfma_f32_16x16x32_bf16 v[72:75], v[154:157], v[206:209], v[72:75]
	s_setprio 0
	s_setprio 1
	v_mfma_f32_16x16x32_bf16 v[116:119], v[158:161], v[178:181], v[116:119]
	v_mfma_f32_16x16x32_bf16 v[112:115], v[166:169], v[178:181], v[112:115]
	v_mfma_f32_16x16x32_bf16 v[100:103], v[158:161], v[186:189], v[100:103]
	v_mfma_f32_16x16x32_bf16 v[96:99], v[166:169], v[186:189], v[96:99]
	v_mfma_f32_16x16x32_bf16 v[84:87], v[158:161], v[194:197], v[84:87]
	v_mfma_f32_16x16x32_bf16 v[80:83], v[166:169], v[194:197], v[80:83]
	v_mfma_f32_16x16x32_bf16 v[68:71], v[158:161], v[202:205], v[68:71]
	v_mfma_f32_16x16x32_bf16 v[64:67], v[166:169], v[202:205], v[64:67]
	v_mfma_f32_16x16x32_bf16 v[116:119], v[162:165], v[182:185], v[116:119]
	v_mfma_f32_16x16x32_bf16 v[112:115], v[170:173], v[182:185], v[112:115]
	v_mfma_f32_16x16x32_bf16 v[100:103], v[162:165], v[190:193], v[100:103]
	v_mfma_f32_16x16x32_bf16 v[96:99], v[170:173], v[190:193], v[96:99]
	v_mfma_f32_16x16x32_bf16 v[84:87], v[162:165], v[198:201], v[84:87]
	v_mfma_f32_16x16x32_bf16 v[80:83], v[170:173], v[198:201], v[80:83]
	v_mfma_f32_16x16x32_bf16 v[68:71], v[162:165], v[206:209], v[68:71]
	v_mfma_f32_16x16x32_bf16 v[64:67], v[170:173], v[206:209], v[64:67]
	s_setprio 0
	s_barrier
	s_add_i32 s55, s55, s2
	v_lshl_add_u64 v[174:175], s[48:49], 0, v[176:177]
	s_mov_b32 m0, s55
	ds_read_b128 v[178:181], v149 offset:16384
	ds_read_b128 v[182:185], v149 offset:17408
	ds_read_b128 v[186:189], v149 offset:18432
	ds_read_b128 v[190:193], v149 offset:19456
	ds_read_b128 v[194:197], v149 offset:20480
	ds_read_b128 v[198:201], v149 offset:21504
	ds_read_b128 v[202:205], v149 offset:22528
	ds_read_b128 v[206:209], v149 offset:23552
	global_load_lds_dwordx4 v[174:175], off
	s_add_i32 m0, s55, 0x2000
	s_add_u32 s56, s48, 0x80000
	v_lshl_add_u64 v[210:211], s[48:49], 0, v[132:133]
	s_addc_u32 s57, s49, 0
	s_add_i32 s55, s58, s2
	global_load_lds_dwordx4 v[210:211], off
	v_lshl_add_u64 v[212:213], s[56:57], 0, v[176:177]
	s_mov_b32 m0, s55
	v_lshl_add_u64 v[214:215], s[50:51], 0, v[130:131]
	global_load_lds_dwordx4 v[212:213], off
	v_lshl_add_u64 v[212:213], s[56:57], 0, v[132:133]
	s_add_i32 m0, s55, 0x2000
	s_nop 0
	global_load_lds_dwordx4 v[212:213], off
	v_lshl_add_u64 v[212:213], s[50:51], 0, v[128:129]
	s_mov_b32 m0, s3
	s_nop 0
	global_load_lds_dwordx4 v[212:213], off
	s_mov_b32 m0, s22
	s_nop 0
	global_load_lds_dwordx4 v[214:215], off
	s_waitcnt vmcnt(8)
	s_waitcnt lgkmcnt(0)
	s_barrier
; #define PG8_STAGE(bufoff, gbase, voff) do { _Pragma("unroll") for (int _i = 0; _i < 2; ++_i) \
;         __builtin_amdgcn_global_load_lds((const unsigned*)((const char*)(gbase) + (voff)[_i]), (PG8_LAS unsigned*)(lds + (bufoff) + ldsw + _i * 8192), 16, 0, 0); } while (0)
; #define PG8_LDA(dst, b, h) do { _Pragma("unroll") for (int m = 0; m < 4; ++m) _Pragma("unroll") for (int k = 0; k < 2; ++k) dst[m][k] = *(const PG8_LAS bf16x8*)(lds + PG8_SA(b, h) + aoff + m * 2048 + k * 1024); } while (0)
; #define PG8_LDB(dst, b, h) do { _Pragma("unroll") for (int n = 0; n < 2; ++n) _Pragma("unroll") for (int k = 0; k < 2; ++k) dst[n][k] = *(const PG8_LAS bf16x8*)(lds + PG8_SB(b, h) + boff + n * 2048 + k * 1024); } while (0)
; #define PG8_MMA(ai, bj, At, Bt) do { __builtin_amdgcn_s_setprio(1); _Pragma("unroll") for (int m = 0; m < 4; ++m) _Pragma("unroll") for (int n = 0; n < 2; ++n) _Pragma("unroll") for (int k = 0; k < 2; ++k) \
;         acc[ai][bj][m][n] = __builtin_amdgcn_mfma_f32_16x16x32_bf16(Bt[n][k], At[m][k], acc[ai][bj][m][n], 0, 0, 0); __builtin_amdgcn_s_setprio(0); } while (0)
; #define PG8_WAIT_V(n) asm volatile("s_waitcnt vmcnt(" #n ")" ::: "memory")
; #define PG8_WAIT_L(n) asm volatile("s_waitcnt lgkmcnt(" #n ")" ::: "memory")
; #define PG8_BAR __builtin_amdgcn_s_barrier()
; #define PG8_SCHED __builtin_amdgcn_sched_barrier(0)
; template <class Epi, class Sched, bool ALIGN_EPI = false, bool SP2 = false>
; __device__ __forceinline__ void gemm_phase(PG8_LAS unsigned char* lds, const Gemm g, const Sched& S, const Epi& E, int wv) {
;     ...
;             PG8_WAIT_V(8); PG8_WAIT_L(0); PG8_BAR; PG8_MMA(0, 0, At, B0); PG8_MMA(0, 1, At, B1); PG8_BAR; PG8_SCHED;
;             PG8_LDA(At, 0, 1); PG8_STAGE(PG8_SB(0, 0), b2, voffB); PG8_STAGE(PG8_SB(0, 1), b2 + hstep, voffB); PG8_STAGE(PG8_SA(0, 0), a2, voffA);
;             PG8_WAIT_V(8); PG8_WAIT_L(0); PG8_BAR; PG8_MMA(1, 0, At, B0); PG8_MMA(1, 1, At, B1); PG8_BAR; PG8_SCHED;
;             PG8_LDB(B0, 1, 0); PG8_LDB(B1, 1, 1); PG8_SCHED; PG8_LDA(At, 1, 0); PG8_STAGE(PG8_SA(0, 1), a2 + hstep, voffA);
;             PG8_WAIT_V(8); PG8_WAIT_L(0); PG8_BAR; PG8_MMA(0, 0, At, B0); PG8_MMA(0, 1, At, B1); PG8_BAR; PG8_SCHED;
;             PG8_LDA(At, 1, 1); PG8_STAGE(PG8_SB(1, 0), b3, voffB); PG8_STAGE(PG8_SB(1, 1), b3 + hstep, voffB); PG8_STAGE(PG8_SA(1, 0), a3, voffA);
	s_setprio 1
	s_waitcnt lgkmcnt(0)
	v_mfma_f32_16x16x32_bf16 v[60:63], v[138:141], v[178:181], v[60:63]
	v_mfma_f32_16x16x32_bf16 v[56:59], v[150:153], v[178:181], v[56:59]
	v_mfma_f32_16x16x32_bf16 v[44:47], v[138:141], v[186:189], v[44:47]
	v_mfma_f32_16x16x32_bf16 v[40:43], v[150:153], v[186:189], v[40:43]
	v_mfma_f32_16x16x32_bf16 v[28:31], v[138:141], v[194:197], v[28:31]
	v_mfma_f32_16x16x32_bf16 v[24:27], v[150:153], v[194:197], v[24:27]
	v_mfma_f32_16x16x32_bf16 v[12:15], v[138:141], v[202:205], v[12:15]
	v_mfma_f32_16x16x32_bf16 v[8:11], v[150:153], v[202:205], v[8:11]
	v_mfma_f32_16x16x32_bf16 v[60:63], v[142:145], v[182:185], v[60:63]
	v_mfma_f32_16x16x32_bf16 v[56:59], v[154:157], v[182:185], v[56:59]
	v_mfma_f32_16x16x32_bf16 v[44:47], v[142:145], v[190:193], v[44:47]
	v_mfma_f32_16x16x32_bf16 v[40:43], v[154:157], v[190:193], v[40:43]
	v_mfma_f32_16x16x32_bf16 v[28:31], v[142:145], v[198:201], v[28:31]
	v_mfma_f32_16x16x32_bf16 v[24:27], v[154:157], v[198:201], v[24:27]
	v_mfma_f32_16x16x32_bf16 v[12:15], v[142:145], v[206:209], v[12:15]
	v_mfma_f32_16x16x32_bf16 v[8:11], v[154:157], v[206:209], v[8:11]
	s_setprio 0
	s_setprio 1
	v_mfma_f32_16x16x32_bf16 v[52:55], v[158:161], v[178:181], v[52:55]
	v_mfma_f32_16x16x32_bf16 v[48:51], v[166:169], v[178:181], v[48:51]
	v_mfma_f32_16x16x32_bf16 v[36:39], v[158:161], v[186:189], v[36:39]
	v_mfma_f32_16x16x32_bf16 v[32:35], v[166:169], v[186:189], v[32:35]
	v_mfma_f32_16x16x32_bf16 v[20:23], v[158:161], v[194:197], v[20:23]
	v_mfma_f32_16x16x32_bf16 v[16:19], v[166:169], v[194:197], v[16:19]
	v_mfma_f32_16x16x32_bf16 v[4:7], v[158:161], v[202:205], v[4:7]
	v_mfma_f32_16x16x32_bf16 v[0:3], v[166:169], v[202:205], v[0:3]
	v_mfma_f32_16x16x32_bf16 v[52:55], v[162:165], v[182:185], v[52:55]
	v_mfma_f32_16x16x32_bf16 v[48:51], v[170:173], v[182:185], v[48:51]
	v_mfma_f32_16x16x32_bf16 v[36:39], v[162:165], v[190:193], v[36:39]
	v_mfma_f32_16x16x32_bf16 v[32:35], v[170:173], v[190:193], v[32:35]
	v_mfma_f32_16x16x32_bf16 v[20:23], v[162:165], v[198:201], v[20:23]
	v_mfma_f32_16x16x32_bf16 v[16:19], v[170:173], v[198:201], v[16:19]
	v_mfma_f32_16x16x32_bf16 v[4:7], v[162:165], v[206:209], v[4:7]
	v_mfma_f32_16x16x32_bf16 v[0:3], v[170:173], v[206:209], v[0:3]
	s_setprio 0
	s_barrier
	s_add_i32 s55, 0, 0x18000
	s_add_i32 s56, 0, 0x1c000
	v_add_u32_e32 v154, s55, v147
	v_add_u32_e32 v170, s56, v147
	ds_read_b128 v[138:141], v154
	ds_read_b128 v[142:145], v154 offset:1024
	ds_read_b128 v[150:153], v154 offset:2048
	ds_read_b128 v[154:157], v154 offset:3072
	ds_read_b128 v[158:161], v170
	ds_read_b128 v[162:165], v170 offset:1024
	ds_read_b128 v[166:169], v170 offset:2048
	ds_read_b128 v[170:173], v170 offset:3072
	s_add_u32 s50, s50, 0x80000
	s_addc_u32 s51, s51, 0
	s_mov_b32 m0, s23
	v_lshl_add_u64 v[216:217], s[50:51], 0, v[128:129]
	ds_read_b128 v[178:181], v149 offset:32768
	ds_read_b128 v[182:185], v149 offset:33792
	ds_read_b128 v[186:189], v149 offset:34816
	ds_read_b128 v[190:193], v149 offset:35840
	ds_read_b128 v[194:197], v149 offset:36864
	ds_read_b128 v[198:201], v149 offset:37888
	ds_read_b128 v[202:205], v149 offset:38912
	ds_read_b128 v[206:209], v149 offset:39936
	global_load_lds_dwordx4 v[216:217], off
	v_lshl_add_u64 v[216:217], s[50:51], 0, v[130:131]
	s_mov_b32 m0, s24
	s_nop 0
	global_load_lds_dwordx4 v[216:217], off
	s_waitcnt vmcnt(8)
	s_waitcnt lgkmcnt(0)
	s_barrier
	s_setprio 1
	s_waitcnt lgkmcnt(0)
	v_mfma_f32_16x16x32_bf16 v[124:127], v[138:141], v[178:181], v[124:127]
	v_mfma_f32_16x16x32_bf16 v[120:123], v[150:153], v[178:181], v[120:123]
	v_mfma_f32_16x16x32_bf16 v[108:111], v[138:141], v[186:189], v[108:111]
	v_mfma_f32_16x16x32_bf16 v[104:107], v[150:153], v[186:189], v[104:107]
	v_mfma_f32_16x16x32_bf16 v[92:95], v[138:141], v[194:197], v[92:95]
	v_mfma_f32_16x16x32_bf16 v[88:91], v[150:153], v[194:197], v[88:91]
	v_mfma_f32_16x16x32_bf16 v[76:79], v[138:141], v[202:205], v[76:79]
	v_mfma_f32_16x16x32_bf16 v[72:75], v[150:153], v[202:205], v[72:75]
	v_mfma_f32_16x16x32_bf16 v[124:127], v[142:145], v[182:185], v[124:127]
	v_mfma_f32_16x16x32_bf16 v[120:123], v[154:157], v[182:185], v[120:123]
	v_mfma_f32_16x16x32_bf16 v[108:111], v[142:145], v[190:193], v[108:111]
	v_mfma_f32_16x16x32_bf16 v[104:107], v[154:157], v[190:193], v[104:107]
	v_mfma_f32_16x16x32_bf16 v[92:95], v[142:145], v[198:201], v[92:95]
	v_mfma_f32_16x16x32_bf16 v[88:91], v[154:157], v[198:201], v[88:91]
	v_mfma_f32_16x16x32_bf16 v[76:79], v[142:145], v[206:209], v[76:79]
	v_mfma_f32_16x16x32_bf16 v[72:75], v[154:157], v[206:209], v[72:75]
	s_setprio 0
	s_setprio 1
	v_mfma_f32_16x16x32_bf16 v[116:119], v[158:161], v[178:181], v[116:119]
	v_mfma_f32_16x16x32_bf16 v[112:115], v[166:169], v[178:181], v[112:115]
	v_mfma_f32_16x16x32_bf16 v[100:103], v[158:161], v[186:189], v[100:103]
	v_mfma_f32_16x16x32_bf16 v[96:99], v[166:169], v[186:189], v[96:99]
	v_mfma_f32_16x16x32_bf16 v[84:87], v[158:161], v[194:197], v[84:87]
	v_mfma_f32_16x16x32_bf16 v[80:83], v[166:169], v[194:197], v[80:83]
	v_mfma_f32_16x16x32_bf16 v[68:71], v[158:161], v[202:205], v[68:71]
	v_mfma_f32_16x16x32_bf16 v[64:67], v[166:169], v[202:205], v[64:67]
	v_mfma_f32_16x16x32_bf16 v[116:119], v[162:165], v[182:185], v[116:119]
	v_mfma_f32_16x16x32_bf16 v[112:115], v[170:173], v[182:185], v[112:115]
	v_mfma_f32_16x16x32_bf16 v[100:103], v[162:165], v[190:193], v[100:103]
	v_mfma_f32_16x16x32_bf16 v[96:99], v[170:173], v[190:193], v[96:99]
	v_mfma_f32_16x16x32_bf16 v[84:87], v[162:165], v[198:201], v[84:87]
	v_mfma_f32_16x16x32_bf16 v[80:83], v[170:173], v[198:201], v[80:83]
	v_mfma_f32_16x16x32_bf16 v[68:71], v[162:165], v[206:209], v[68:71]
	v_mfma_f32_16x16x32_bf16 v[64:67], v[170:173], v[206:209], v[64:67]
	s_setprio 0
	s_barrier
; #define PG8_STAGE(bufoff, gbase, voff) do { _Pragma("unroll") for (int _i = 0; _i < 2; ++_i) \
;         __builtin_amdgcn_global_load_lds((const unsigned*)((const char*)(gbase) + (voff)[_i]), (PG8_LAS unsigned*)(lds + (bufoff) + ldsw + _i * 8192), 16, 0, 0); } while (0)
; #define PG8_LDA(dst, b, h) do { _Pragma("unroll") for (int m = 0; m < 4; ++m) _Pragma("unroll") for (int k = 0; k < 2; ++k) dst[m][k] = *(const PG8_LAS bf16x8*)(lds + PG8_SA(b, h) + aoff + m * 2048 + k * 1024); } while (0)
; #define PG8_LDB(dst, b, h) do { _Pragma("unroll") for (int n = 0; n < 2; ++n) _Pragma("unroll") for (int k = 0; k < 2; ++k) dst[n][k] = *(const PG8_LAS bf16x8*)(lds + PG8_SB(b, h) + boff + n * 2048 + k * 1024); } while (0)
; template <class Epi, class Sched, bool ALIGN_EPI = false, bool SP2 = false>
; __device__ __forceinline__ void gemm_phase(PG8_LAS unsigned char* lds, const Gemm g, const Sched& S, const Epi& E, int wv) {
;     ...
;         for (int t = 0; t < nt; t += 2) {
;             const bool last = (t == nt - 2);
;             const char* a1 = cA + (size_t)(t + 1) * kstep;
;             const char* a2 = last ? nA : cA + (size_t)(t + 2) * kstep; const char* b2 = last ? nB : cB + (size_t)(t + 2) * kstep;
;             const char* a3 = a2 + kstep; const char* b3 = b2 + kstep;
;             if (last && has_next) S.a_ready(nxt);
;             if constexpr (SP2) {
;             PG8_LDB(B0, 0, 0); PG8_LDB(B1, 0, 1); PG8_SCHED; PG8_LDA(At, 0, 0); PG8_STAGE(PG8_SA(1, 1), a1 + hstep, voffA);
;             PG8_WAIT_V(8); PG8_WAIT_L(0); PG8_BAR; PG8_MMA(0, 0, At, B0); PG8_MMA(0, 1, At, B1); PG8_BAR; PG8_SCHED;
;             PG8_LDA(At, 0, 1); PG8_STAGE(PG8_SB(0, 0), b2, voffB); PG8_STAGE(PG8_SB(0, 1), b2 + hstep, voffB); PG8_STAGE(PG8_SA(0, 0), a2, voffA);
;             PG8_WAIT_V(8); PG8_WAIT_L(0); PG8_BAR; PG8_MMA(1, 0, At, B0); PG8_MMA(1, 1, At, B1); PG8_BAR; PG8_SCHED;
;             PG8_LDB(B0, 1, 0); PG8_LDB(B1, 1, 1); PG8_SCHED; PG8_LDA(At, 1, 0); PG8_STAGE(PG8_SA(0, 1), a2 + hstep, voffA);
;             PG8_WAIT_V(8); PG8_WAIT_L(0); PG8_BAR; PG8_MMA(0, 0, At, B0); PG8_MMA(0, 1, At, B1); PG8_BAR; PG8_SCHED;
;             PG8_LDA(At, 1, 1); PG8_STAGE(PG8_SB(1, 0), b3, voffB); PG8_STAGE(PG8_SB(1, 1), b3 + hstep, voffB); PG8_STAGE(PG8_SA(1, 0), a3, voffA);
;             PG8_WAIT_V(8); PG8_WAIT_L(0); PG8_BAR; PG8_MMA(1, 0, At, B0); PG8_MMA(1, 1, At, B1); PG8_BAR; PG8_SCHED;
	s_add_i32 s50, s55, s2
	v_lshl_add_u64 v[174:175], v[174:175], 0, s[28:29]
	s_mov_b32 m0, s50
	ds_read_b128 v[178:181], v149 offset:49152
	ds_read_b128 v[182:185], v149 offset:50176
	ds_read_b128 v[186:189], v149 offset:51200
	ds_read_b128 v[190:193], v149 offset:52224
	ds_read_b128 v[194:197], v149 offset:53248
	ds_read_b128 v[198:201], v149 offset:54272
	ds_read_b128 v[202:205], v149 offset:55296
	ds_read_b128 v[206:209], v149 offset:56320
	global_load_lds_dwordx4 v[174:175], off
	s_add_i32 m0, s50, 0x2000
	s_add_u32 s48, s48, 0x80080
	v_lshl_add_u64 v[174:175], v[210:211], 0, s[28:29]
	s_addc_u32 s49, s49, 0
	s_add_i32 s50, s56, s2
	global_load_lds_dwordx4 v[174:175], off
	v_lshl_add_u64 v[174:175], s[48:49], 0, v[176:177]
	s_mov_b32 m0, s50
	s_nop 0
	global_load_lds_dwordx4 v[174:175], off
	v_lshl_add_u64 v[174:175], s[48:49], 0, v[132:133]
	s_add_i32 m0, s50, 0x2000
	s_nop 0
	global_load_lds_dwordx4 v[174:175], off
	v_lshl_add_u64 v[174:175], v[212:213], 0, s[28:29]
	s_mov_b32 m0, s27
	s_nop 0
	global_load_lds_dwordx4 v[174:175], off
	v_lshl_add_u64 v[174:175], v[214:215], 0, s[28:29]
	s_mov_b32 m0, s30
	s_nop 0
	global_load_lds_dwordx4 v[174:175], off
	s_waitcnt vmcnt(8)
	s_waitcnt lgkmcnt(0)
	s_barrier
	s_setprio 1
	s_waitcnt lgkmcnt(0)
	v_mfma_f32_16x16x32_bf16 v[60:63], v[138:141], v[178:181], v[60:63]
	v_mfma_f32_16x16x32_bf16 v[56:59], v[150:153], v[178:181], v[56:59]
	v_mfma_f32_16x16x32_bf16 v[44:47], v[138:141], v[186:189], v[44:47]
	v_mfma_f32_16x16x32_bf16 v[40:43], v[150:153], v[186:189], v[40:43]
	v_mfma_f32_16x16x32_bf16 v[28:31], v[138:141], v[194:197], v[28:31]
	v_mfma_f32_16x16x32_bf16 v[24:27], v[150:153], v[194:197], v[24:27]
	v_mfma_f32_16x16x32_bf16 v[12:15], v[138:141], v[202:205], v[12:15]
	v_mfma_f32_16x16x32_bf16 v[8:11], v[150:153], v[202:205], v[8:11]
	v_mfma_f32_16x16x32_bf16 v[60:63], v[142:145], v[182:185], v[60:63]
	v_mfma_f32_16x16x32_bf16 v[56:59], v[154:157], v[182:185], v[56:59]
	v_mfma_f32_16x16x32_bf16 v[44:47], v[142:145], v[190:193], v[44:47]
	v_mfma_f32_16x16x32_bf16 v[40:43], v[154:157], v[190:193], v[40:43]
	v_mfma_f32_16x16x32_bf16 v[28:31], v[142:145], v[198:201], v[28:31]
	v_mfma_f32_16x16x32_bf16 v[24:27], v[154:157], v[198:201], v[24:27]
	v_mfma_f32_16x16x32_bf16 v[12:15], v[142:145], v[206:209], v[12:15]
	v_mfma_f32_16x16x32_bf16 v[8:11], v[154:157], v[206:209], v[8:11]
	s_setprio 0
	s_setprio 1
	v_mfma_f32_16x16x32_bf16 v[52:55], v[158:161], v[178:181], v[52:55]
	v_mfma_f32_16x16x32_bf16 v[48:51], v[166:169], v[178:181], v[48:51]
	v_mfma_f32_16x16x32_bf16 v[36:39], v[158:161], v[186:189], v[36:39]
	v_mfma_f32_16x16x32_bf16 v[32:35], v[166:169], v[186:189], v[32:35]
	v_mfma_f32_16x16x32_bf16 v[20:23], v[158:161], v[194:197], v[20:23]
	v_mfma_f32_16x16x32_bf16 v[16:19], v[166:169], v[194:197], v[16:19]
	v_mfma_f32_16x16x32_bf16 v[4:7], v[158:161], v[202:205], v[4:7]
	v_mfma_f32_16x16x32_bf16 v[0:3], v[166:169], v[202:205], v[0:3]
	v_mfma_f32_16x16x32_bf16 v[52:55], v[162:165], v[182:185], v[52:55]
	v_mfma_f32_16x16x32_bf16 v[48:51], v[170:173], v[182:185], v[48:51]
	v_mfma_f32_16x16x32_bf16 v[36:39], v[162:165], v[190:193], v[36:39]
	v_mfma_f32_16x16x32_bf16 v[32:35], v[170:173], v[190:193], v[32:35]
	v_mfma_f32_16x16x32_bf16 v[20:23], v[162:165], v[198:201], v[20:23]
	v_mfma_f32_16x16x32_bf16 v[16:19], v[170:173], v[198:201], v[16:19]
	v_mfma_f32_16x16x32_bf16 v[4:7], v[162:165], v[206:209], v[4:7]
	v_mfma_f32_16x16x32_bf16 v[0:3], v[170:173], v[206:209], v[0:3]
	s_setprio 0
	s_barrier
	s_add_i32 s54, s54, 2
	s_add_u32 s40, s40, 0x100
	s_addc_u32 s41, s41, 0
	s_add_u32 s52, s52, 0x100
	s_addc_u32 s53, s53, 0
	s_cmp_gt_u32 s54, 29
	s_cbranch_scc0 .LBB0_343
	s_and_b64 vcc, exec, s[16:17]
	s_cbranch_vccz .LBB0_346
	s_barrier
